# lean4 + merge epilogue: second batch of RMW loads issued early (each right after its register quad is consumed in the first half), exact counted vmcnt waits
# speedup vs baseline: 1.0024x; 1.0012x over previous
; __device__ __forceinline__ size_t tl(int row, int col, int K) { return (size_t)(row >> 8) * ((size_t)256 * K) + (size_t)(col >> 6) * (256 * 64) + (size_t)((row & 255) * 64 + (col & 63)); }
;     __device__ __forceinline__ void operator()(const f32x4 (&acc)[2][2][4][2], const Unit& u, int wr, int wc, int, int) const {
;     ...
;         const int br = u.pm >> 6, pm = u.pm & 63, pn = u.pn & 3, gb = br < 2 ? br : 2;
;         const unsigned char* Zg = (const unsigned char*)Z + ZGATE_B + gb * 1024;
;         const int row0 = pm * BM + wr * 64 + fr, col0 = pn * BM + wc * 32 + 8 * fq;
;         v2u gq[2][4][2];
; #pragma unroll
;         for (int ai = 0; ai < 2; ++ai)
; #pragma unroll
;             for (int m = 0; m < 4; ++m)
; #pragma unroll
;                 for (int bj = 0; bj < 2; ++bj) gq[ai][m][bj] = *(const v2u*)(Zg + (size_t)(row0 + ai * HALF + m * 16) * ZPB + col0 + bj * HALF);
; #pragma unroll
;         for (int ai = 0; ai < 2; ++ai) {
;             u32x4 mo[4][2];
;             if (br != 0) {
; #pragma unroll
;                 for (int m = 0; m < 4; ++m)
; #pragma unroll
;                     for (int bj = 0; bj < 2; ++bj) mo[m][bj] = *(const u32x4*)(Mg + tl(row0 + ai * HALF + m * 16, col0 + bj * HALF, DM));
;             }
;             asm volatile("" ::: "memory");
; #pragma unroll
;             for (int m = 0; m < 4; ++m) {
;                 const int row = row0 + ai * HALF + m * 16;
; #pragma unroll
;                 for (int bj = 0; bj < 2; ++bj) {
;                     float g[8], o[8];
;                     { const v2u q = gq[ai][m][bj]; const float k = 1.0f / 255.0f;
;                       g[0] = (float)(q.x & 255u) * k; g[1] = (float)((q.x >> 8) & 255u) * k; g[2] = (float)((q.x >> 16) & 255u) * k; g[3] = (float)(q.x >> 24) * k;
;                       g[4] = (float)(q.y & 255u) * k; g[5] = (float)((q.y >> 8) & 255u) * k; g[6] = (float)((q.y >> 16) & 255u) * k; g[7] = (float)(q.y >> 24) * k; }
; #pragma unroll
;                     for (int n = 0; n < 2; ++n)
; #pragma unroll
;                         for (int i = 0; i < 4; ++i) o[n * 4 + i] = g[n * 4 + i] * acc[ai][bj][m][n][i];
.LBB0_907:
	s_and_b32 s5, s4, 0xffffffc0
	s_cmpk_lg_i32 s5, 0x80
	s_cselect_b64 s[18:19], -1, 0
	s_cmpk_eq_i32 s5, 0x80
	s_movk_i32 s80, 0x2000
	s_mov_b32 s81, 0x10000
	s_cbranch_scc1 .LBB0_945
	s_ashr_i32 s5, s4, 6
	s_min_i32 s5, s5, 2
	s_lshl_b32 s5, s5, 10
	s_ashr_i32 s11, s5, 31
	s_add_u32 s64, s53, s5
	s_addc_u32 s65, s54, s11
	s_lshl_b32 s5, s4, 8
	v_mov_b32_e32 v128, v230
	s_and_b32 s5, s5, 0x3f00
	s_lshl_b32 s11, s20, 8
	s_add_i32 s5, s5, s42
	s_and_b32 s11, s11, 0x300
	v_and_or_b32 v134, v128, 15, s5
	s_or_b32 s11, s11, s50
	v_lshrrev_b32_e32 v128, 1, v128
	v_and_or_b32 v220, v128, 24, s11
	v_lshl_add_u64 v[128:129], s[64:65], 0, v[220:221]
	v_or_b32_e32 v132, 16, v134
	v_mad_i64_i32 v[130:131], s[20:21], v134, s29, v[128:129]
	v_mad_i64_i32 v[132:133], s[20:21], v132, s29, v[128:129]
	global_load_dwordx2 v[198:199], v[130:131], off
	global_load_dwordx2 v[190:191], v[130:131], off offset:128
	global_load_dwordx2 v[196:197], v[132:133], off
	global_load_dwordx2 v[194:195], v[132:133], off offset:128
	v_or_b32_e32 v130, 32, v134
	v_or_b32_e32 v132, 48, v134
	v_mad_i64_i32 v[130:131], s[20:21], v130, s29, v[128:129]
	v_mad_i64_i32 v[132:133], s[20:21], v132, s29, v[128:129]
	v_add_u32_e32 v208, 0x80, v134
	global_load_dwordx2 v[192:193], v[130:131], off
	global_load_dwordx2 v[188:189], v[130:131], off offset:128
	global_load_dwordx2 v[186:187], v[132:133], off
	global_load_dwordx2 v[184:185], v[132:133], off offset:128
	v_mad_i64_i32 v[130:131], s[20:21], v208, s29, v[128:129]
	v_add_u32_e32 v132, 0x90, v134
	v_mad_i64_i32 v[132:133], s[20:21], v132, s29, v[128:129]
	global_load_dwordx2 v[182:183], v[130:131], off
	global_load_dwordx2 v[180:181], v[130:131], off offset:128
	global_load_dwordx2 v[178:179], v[132:133], off
	global_load_dwordx2 v[176:177], v[132:133], off offset:128
	v_add_u32_e32 v130, 0xa0, v134
	v_mad_i64_i32 v[130:131], s[20:21], v130, s29, v[128:129]
	v_add_u32_e32 v132, 0xb0, v134
	v_mad_i64_i32 v[128:129], s[20:21], v132, s29, v[128:129]
	global_load_dwordx2 v[174:175], v[130:131], off
	global_load_dwordx2 v[172:173], v[130:131], off offset:128
	global_load_dwordx2 v[170:171], v[128:129], off
	global_load_dwordx2 v[168:169], v[128:129], off offset:128
	s_cmp_gt_u32 s4, 63
	s_cselect_b64 s[66:67], -1, 0
	s_ashr_i32 s20, s5, 8
	s_ashr_i32 s21, s20, 31
	s_lshl_b32 s11, s11, 8
	s_lshl_b64 s[20:21], s[20:21], 19
	s_cmp_lt_u32 s4, 64
	v_mov_b32_e32 v128, s11
	s_mov_b32 s4, 0x34038
	v_bitop3_b32 v209, v220, s4, v128 bitop3:0xc8
	v_lshlrev_b32_e32 v128, 6, v134
	v_and_or_b32 v128, v128, s84, v209
	v_lshlrev_b32_e32 v220, 1, v128
	s_cbranch_scc1 .LBB0_910
	s_add_u32 s4, s6, s20
	s_addc_u32 s5, s7, s21
	v_lshl_add_u64 v[128:129], s[4:5], 0, v[220:221]
	v_add_co_u32_e32 v130, vcc, 0x10000, v128
	s_nop 1
	v_addc_co_u32_e32 v131, vcc, 0, v129, vcc
	global_load_dwordx4 v[156:159], v220, s[4:5]
	global_load_dwordx4 v[148:151], v220, s[4:5] offset:2048
	global_load_dwordx4 v[152:155], v[130:131], off
	global_load_dwordx4 v[144:147], v[130:131], off offset:2048
	v_add_co_u32_e32 v130, vcc, 0x1000, v128
	s_nop 1
	v_addc_co_u32_e32 v131, vcc, 0, v129, vcc
	v_add_co_u32_e32 v128, vcc, 0x11000, v128
	s_nop 1
	v_addc_co_u32_e32 v129, vcc, 0, v129, vcc
	global_load_dwordx4 v[140:143], v[130:131], off
	global_load_dwordx4 v[132:135], v[130:131], off offset:2048
	global_load_dwordx4 v[136:139], v[128:129], off
	s_nop 0
	global_load_dwordx4 v[128:131], v[128:129], off offset:2048
	v_ashrrev_i32_e32 v222, 8, v208
	v_lshlrev_b32_e32 v224, 6, v208
	v_ashrrev_i32_e32 v223, 31, v222
	v_and_or_b32 v224, v224, s84, v209
	v_lshlrev_b64 v[222:223], 19, v[222:223]
	v_lshlrev_b32_e32 v224, 1, v224
	v_mov_b32_e32 v225, v221
	v_lshl_add_u64 v[222:223], s[6:7], 0, v[222:223]
	v_lshl_add_u64 v[222:223], v[222:223], 0, v[224:225]
	v_add_co_u32_e32 v224, vcc, 0x10000, v222
	s_nop 1
	v_addc_co_u32_e32 v225, vcc, 0, v223, vcc
	v_add_co_u32_e32 v226, vcc, 0x1000, v222
	s_nop 1
	v_addc_co_u32_e32 v227, vcc, 0, v223, vcc
	v_add_co_u32_e32 v228, vcc, 0x11000, v222
	s_nop 1
	v_addc_co_u32_e32 v229, vcc, 0, v223, vcc
.LBB0_910:
	s_waitcnt vmcnt(0)
	v_cvt_f32_ubyte1_e32 v201, v198
	v_cvt_f32_ubyte0_e32 v200, v198
	v_cvt_f32_ubyte3_e32 v203, v198
	v_cvt_f32_ubyte2_e32 v202, v198
	v_cvt_f32_ubyte1_e32 v205, v199
	v_cvt_f32_ubyte0_e32 v204, v199
	v_cvt_f32_ubyte3_e32 v211, v199
	v_cvt_f32_ubyte2_e32 v210, v199
	v_pk_mul_f32 v[200:201], v[200:201], s[36:37] op_sel_hi:[1,0]
	v_pk_mul_f32 v[202:203], v[202:203], s[36:37] op_sel_hi:[1,0]
	v_pk_mul_f32 v[204:205], v[204:205], s[36:37] op_sel_hi:[1,0]
	v_pk_mul_f32 v[198:199], v[210:211], s[36:37] op_sel_hi:[1,0]
	v_cndmask_b32_e64 v210, 0, 1, s[66:67]
	v_pk_mul_f32 v[200:201], v[124:125], v[200:201]
	v_pk_mul_f32 v[202:203], v[126:127], v[202:203]
	v_pk_mul_f32 v[204:205], v[120:121], v[204:205]
	v_cmp_ne_u32_e64 s[4:5], 1, v210
	s_andn2_b64 vcc, exec, s[66:67]
	v_pk_mul_f32 v[198:199], v[122:123], v[198:199]
	s_cbranch_vccnz .LBB0_912
	v_lshlrev_b32_e32 v210, 16, v156
	v_and_b32_e32 v211, 0xffff0000, v156
	v_pk_add_f32 v[200:201], v[200:201], v[210:211]
	v_lshlrev_b32_e32 v210, 16, v157
	v_and_b32_e32 v211, 0xffff0000, v157
	v_pk_add_f32 v[202:203], v[202:203], v[210:211]
	v_lshlrev_b32_e32 v210, 16, v158
	v_and_b32_e32 v211, 0xffff0000, v158
	v_pk_add_f32 v[204:205], v[204:205], v[210:211]
	v_lshlrev_b32_e32 v210, 16, v159
	v_and_b32_e32 v211, 0xffff0000, v159
	v_pk_add_f32 v[198:199], v[198:199], v[210:211]
	global_load_dwordx4 v[156:159], v[222:223], off

; __device__ __forceinline__ void unpack8(const v4u r, float* x) { x[0] = bflo(r.x); x[1] = bfhi(r.x); x[2] = bflo(r.y); x[3] = bfhi(r.y); x[4] = bflo(r.z); x[5] = bfhi(r.z); x[6] = bflo(r.w); x[7] = bfhi(r.w); }
; __device__ __forceinline__ v4u pack8(const float* x) { v4u o; o.x = pk2(x[0], x[1]); o.y = pk2(x[2], x[3]); o.z = pk2(x[4], x[5]); o.w = pk2(x[6], x[7]); return o; }
; __device__ __forceinline__ size_t tl(int row, int col, int K) { return (size_t)(row >> 8) * ((size_t)256 * K) + (size_t)(col >> 6) * (256 * 64) + (size_t)((row & 255) * 64 + (col & 63)); }
;     __device__ __forceinline__ void operator()(const f32x4 (&acc)[2][2][4][2], const Unit& u, int wr, int wc, int, int) const {
;     ...
;             for (int m = 0; m < 4; ++m) {
;                 const int row = row0 + ai * HALF + m * 16;
; #pragma unroll
;                 for (int bj = 0; bj < 2; ++bj) {
;                     float g[8], o[8];
;                     { const v2u q = gq[ai][m][bj]; const float k = 1.0f / 255.0f;
;                       g[0] = (float)(q.x & 255u) * k; g[1] = (float)((q.x >> 8) & 255u) * k; g[2] = (float)((q.x >> 16) & 255u) * k; g[3] = (float)(q.x >> 24) * k;
;                       g[4] = (float)(q.y & 255u) * k; g[5] = (float)((q.y >> 8) & 255u) * k; g[6] = (float)((q.y >> 16) & 255u) * k; g[7] = (float)(q.y >> 24) * k; }
; #pragma unroll
;                     for (int n = 0; n < 2; ++n)
; #pragma unroll
;                         for (int i = 0; i < 4; ++i) o[n * 4 + i] = g[n * 4 + i] * acc[ai][bj][m][n][i];
;                     if (br != 0) { float p[8]; unpack8(mo[m][bj], p);
; #pragma unroll
;                         for (int i = 0; i < 8; ++i) o[i] += p[i]; }
;                     *(u32x4*)(Mg + tl(row, col0 + bj * HALF, DM)) = pack8(o);
;                 }
.LBB0_914:
	v_lshl_add_u64 v[190:191], s[20:21], 0, v[220:221]
	v_cvt_pk_bf16_f32 v210, v198, v199
	v_add_co_u32_e32 v198, vcc, s81, v190
	v_cvt_pk_bf16_f32 v211, v200, v201
	v_cvt_pk_bf16_f32 v212, v202, v203
	v_cvt_pk_bf16_f32 v213, v204, v205
	v_addc_co_u32_e32 v199, vcc, 0, v191, vcc
	global_store_dwordx4 v[198:199], v[210:213], off
	v_cvt_f32_ubyte1_e32 v201, v196
	v_cvt_f32_ubyte0_e32 v200, v196
	v_cvt_f32_ubyte3_e32 v203, v196
	v_cvt_f32_ubyte2_e32 v202, v196
	v_cvt_f32_ubyte1_e32 v205, v197
	v_cvt_f32_ubyte0_e32 v204, v197
	v_cvt_f32_ubyte3_e32 v211, v197
	v_cvt_f32_ubyte2_e32 v210, v197
	v_pk_mul_f32 v[200:201], v[200:201], s[36:37] op_sel_hi:[1,0]
	v_pk_mul_f32 v[202:203], v[202:203], s[36:37] op_sel_hi:[1,0]
	v_pk_mul_f32 v[204:205], v[204:205], s[36:37] op_sel_hi:[1,0]
	v_pk_mul_f32 v[196:197], v[210:211], s[36:37] op_sel_hi:[1,0]
	v_pk_mul_f32 v[200:201], v[116:117], v[200:201]
	v_pk_mul_f32 v[202:203], v[118:119], v[202:203]
	v_pk_mul_f32 v[204:205], v[112:113], v[204:205]
	s_and_b64 vcc, exec, s[4:5]
	v_pk_mul_f32 v[196:197], v[114:115], v[196:197]
	s_cbranch_vccnz .LBB0_916
	v_lshlrev_b32_e32 v210, 16, v148
	v_and_b32_e32 v211, 0xffff0000, v148
	v_pk_add_f32 v[200:201], v[200:201], v[210:211]
	v_lshlrev_b32_e32 v210, 16, v149
	v_and_b32_e32 v211, 0xffff0000, v149
	v_pk_add_f32 v[202:203], v[202:203], v[210:211]
	v_lshlrev_b32_e32 v210, 16, v150
	v_and_b32_e32 v211, 0xffff0000, v150
	v_pk_add_f32 v[204:205], v[204:205], v[210:211]
	v_lshlrev_b32_e32 v210, 16, v151
	v_and_b32_e32 v211, 0xffff0000, v151
	v_pk_add_f32 v[196:197], v[196:197], v[210:211]
	global_load_dwordx4 v[148:151], v[222:223], off offset:2048
	global_load_dwordx4 v[152:155], v[224:225], off
.LBB0_916:
	v_cvt_pk_bf16_f32 v200, v200, v201
	v_cvt_pk_bf16_f32 v201, v202, v203
	v_cvt_pk_bf16_f32 v202, v204, v205
	v_cvt_pk_bf16_f32 v203, v196, v197
	global_store_dwordx4 v[190:191], v[200:203], off offset:2048
	v_cvt_f32_ubyte1_e32 v197, v194
	v_cvt_f32_ubyte0_e32 v196, v194
	v_cvt_f32_ubyte3_e32 v201, v194
	v_cvt_f32_ubyte2_e32 v200, v194
	v_cvt_f32_ubyte1_e32 v203, v195
	v_cvt_f32_ubyte0_e32 v202, v195
	v_cvt_f32_ubyte3_e32 v205, v195
	v_cvt_f32_ubyte2_e32 v204, v195
	v_pk_mul_f32 v[196:197], v[196:197], s[36:37] op_sel_hi:[1,0]
	v_pk_mul_f32 v[200:201], v[200:201], s[36:37] op_sel_hi:[1,0]
	v_pk_mul_f32 v[202:203], v[202:203], s[36:37] op_sel_hi:[1,0]
	v_pk_mul_f32 v[194:195], v[204:205], s[36:37] op_sel_hi:[1,0]
	v_pk_mul_f32 v[196:197], v[84:85], v[196:197]
	v_pk_mul_f32 v[200:201], v[86:87], v[200:201]
	v_pk_mul_f32 v[202:203], v[80:81], v[202:203]
	s_and_b64 vcc, exec, s[4:5]
	v_pk_mul_f32 v[194:195], v[82:83], v[194:195]
	s_cbranch_vccnz .LBB0_918
	v_lshlrev_b32_e32 v204, 16, v144
	v_and_b32_e32 v205, 0xffff0000, v144
	v_pk_add_f32 v[196:197], v[196:197], v[204:205]
	v_lshlrev_b32_e32 v204, 16, v145
	v_and_b32_e32 v205, 0xffff0000, v145
	v_pk_add_f32 v[200:201], v[200:201], v[204:205]
	v_lshlrev_b32_e32 v204, 16, v146
	v_and_b32_e32 v205, 0xffff0000, v146
	v_pk_add_f32 v[202:203], v[202:203], v[204:205]
	v_lshlrev_b32_e32 v204, 16, v147
	v_and_b32_e32 v205, 0xffff0000, v147
	v_pk_add_f32 v[194:195], v[194:195], v[204:205]
	global_load_dwordx4 v[144:147], v[224:225], off offset:2048
.LBB0_918:
	v_cvt_pk_bf16_f32 v210, v196, v197
	v_cvt_pk_bf16_f32 v211, v200, v201
	v_cvt_pk_bf16_f32 v212, v202, v203
	v_cvt_pk_bf16_f32 v213, v194, v195
	global_store_dwordx4 v[198:199], v[210:213], off offset:2048
	v_cvt_f32_ubyte1_e32 v195, v192
	v_cvt_f32_ubyte0_e32 v194, v192
	v_cvt_f32_ubyte3_e32 v197, v192
	v_cvt_f32_ubyte2_e32 v196, v192
	v_cvt_f32_ubyte1_e32 v199, v193
	v_cvt_f32_ubyte0_e32 v198, v193
	v_cvt_f32_ubyte3_e32 v201, v193
	v_cvt_f32_ubyte2_e32 v200, v193
	v_pk_mul_f32 v[194:195], v[194:195], s[36:37] op_sel_hi:[1,0]
	v_pk_mul_f32 v[196:197], v[196:197], s[36:37] op_sel_hi:[1,0]
	v_pk_mul_f32 v[198:199], v[198:199], s[36:37] op_sel_hi:[1,0]
	v_pk_mul_f32 v[192:193], v[200:201], s[36:37] op_sel_hi:[1,0]
	v_pk_mul_f32 v[194:195], v[108:109], v[194:195]
	v_pk_mul_f32 v[196:197], v[110:111], v[196:197]
	v_pk_mul_f32 v[198:199], v[104:105], v[198:199]
	s_and_b64 vcc, exec, s[4:5]
	v_pk_mul_f32 v[192:193], v[106:107], v[192:193]
	s_cbranch_vccnz .LBB0_920
	v_lshlrev_b32_e32 v200, 16, v140
	v_and_b32_e32 v201, 0xffff0000, v140
	v_pk_add_f32 v[194:195], v[194:195], v[200:201]
	v_lshlrev_b32_e32 v200, 16, v141
	v_and_b32_e32 v201, 0xffff0000, v141
	v_pk_add_f32 v[196:197], v[196:197], v[200:201]
	v_lshlrev_b32_e32 v200, 16, v142
	v_and_b32_e32 v201, 0xffff0000, v142
	v_pk_add_f32 v[198:199], v[198:199], v[200:201]
	v_lshlrev_b32_e32 v200, 16, v143
	v_and_b32_e32 v201, 0xffff0000, v143
	v_pk_add_f32 v[192:193], v[192:193], v[200:201]
	global_load_dwordx4 v[140:143], v[226:227], off

; __device__ __forceinline__ void unpack8(const v4u r, float* x) { x[0] = bflo(r.x); x[1] = bfhi(r.x); x[2] = bflo(r.y); x[3] = bfhi(r.y); x[4] = bflo(r.z); x[5] = bfhi(r.z); x[6] = bflo(r.w); x[7] = bfhi(r.w); }
; __device__ __forceinline__ v4u pack8(const float* x) { v4u o; o.x = pk2(x[0], x[1]); o.y = pk2(x[2], x[3]); o.z = pk2(x[4], x[5]); o.w = pk2(x[6], x[7]); return o; }
; __device__ __forceinline__ size_t tl(int row, int col, int K) { return (size_t)(row >> 8) * ((size_t)256 * K) + (size_t)(col >> 6) * (256 * 64) + (size_t)((row & 255) * 64 + (col & 63)); }
;     __device__ __forceinline__ void operator()(const f32x4 (&acc)[2][2][4][2], const Unit& u, int wr, int wc, int, int) const {
;     ...
;             for (int m = 0; m < 4; ++m) {
;                 const int row = row0 + ai * HALF + m * 16;
; #pragma unroll
;                 for (int bj = 0; bj < 2; ++bj) {
;                     float g[8], o[8];
;                     { const v2u q = gq[ai][m][bj]; const float k = 1.0f / 255.0f;
;                       g[0] = (float)(q.x & 255u) * k; g[1] = (float)((q.x >> 8) & 255u) * k; g[2] = (float)((q.x >> 16) & 255u) * k; g[3] = (float)(q.x >> 24) * k;
;                       g[4] = (float)(q.y & 255u) * k; g[5] = (float)((q.y >> 8) & 255u) * k; g[6] = (float)((q.y >> 16) & 255u) * k; g[7] = (float)(q.y >> 24) * k; }
; #pragma unroll
;                     for (int n = 0; n < 2; ++n)
; #pragma unroll
;                         for (int i = 0; i < 4; ++i) o[n * 4 + i] = g[n * 4 + i] * acc[ai][bj][m][n][i];
;                     if (br != 0) { float p[8]; unpack8(mo[m][bj], p);
; #pragma unroll
;                         for (int i = 0; i < 8; ++i) o[i] += p[i]; }
;                     *(u32x4*)(Mg + tl(row, col0 + bj * HALF, DM)) = pack8(o);
;                 }
.LBB0_922:
	s_mov_b32 s11, 0x11000
	v_cvt_pk_bf16_f32 v194, v194, v195
	v_cvt_pk_bf16_f32 v195, v196, v197
	v_cvt_pk_bf16_f32 v197, v188, v189
	v_add_co_u32_e32 v188, vcc, s11, v190
	v_cvt_pk_bf16_f32 v196, v198, v199
	s_nop 0
	v_addc_co_u32_e32 v189, vcc, 0, v191, vcc
	global_store_dwordx4 v[188:189], v[194:197], off
	v_cvt_f32_ubyte1_e32 v189, v186
	v_cvt_f32_ubyte0_e32 v188, v186
	v_cvt_f32_ubyte3_e32 v195, v186
	v_cvt_f32_ubyte2_e32 v194, v186
	v_cvt_f32_ubyte1_e32 v197, v187
	v_cvt_f32_ubyte0_e32 v196, v187
	v_cvt_f32_ubyte3_e32 v199, v187
	v_cvt_f32_ubyte2_e32 v198, v187
	v_pk_mul_f32 v[188:189], v[188:189], s[36:37] op_sel_hi:[1,0]
	v_pk_mul_f32 v[194:195], v[194:195], s[36:37] op_sel_hi:[1,0]
	v_pk_mul_f32 v[196:197], v[196:197], s[36:37] op_sel_hi:[1,0]
	v_pk_mul_f32 v[186:187], v[198:199], s[36:37] op_sel_hi:[1,0]
	v_pk_mul_f32 v[188:189], v[100:101], v[188:189]
	v_pk_mul_f32 v[194:195], v[102:103], v[194:195]
	v_pk_mul_f32 v[196:197], v[96:97], v[196:197]
	s_and_b64 vcc, exec, s[4:5]
	v_pk_mul_f32 v[186:187], v[98:99], v[186:187]
	s_cbranch_vccnz .LBB0_924
	v_lshlrev_b32_e32 v198, 16, v132
	v_and_b32_e32 v199, 0xffff0000, v132
	v_pk_add_f32 v[188:189], v[188:189], v[198:199]
	v_lshlrev_b32_e32 v198, 16, v133
	v_and_b32_e32 v199, 0xffff0000, v133
	v_pk_add_f32 v[194:195], v[194:195], v[198:199]
	v_lshlrev_b32_e32 v198, 16, v134
	v_and_b32_e32 v199, 0xffff0000, v134
	v_pk_add_f32 v[196:197], v[196:197], v[198:199]
	v_lshlrev_b32_e32 v198, 16, v135
	v_and_b32_e32 v199, 0xffff0000, v135
	v_pk_add_f32 v[186:187], v[186:187], v[198:199]
	global_load_dwordx4 v[132:135], v[226:227], off offset:2048
	global_load_dwordx4 v[136:139], v[228:229], off
.LBB0_924:
	v_cvt_pk_bf16_f32 v198, v188, v189
	v_cvt_pk_bf16_f32 v199, v194, v195
	v_cvt_pk_bf16_f32 v200, v196, v197
	v_cvt_pk_bf16_f32 v201, v186, v187
	global_store_dwordx4 v[192:193], v[198:201], off offset:2048
	v_cvt_f32_ubyte1_e32 v187, v184
	v_cvt_f32_ubyte0_e32 v186, v184
	v_cvt_f32_ubyte3_e32 v189, v184
	v_cvt_f32_ubyte2_e32 v188, v184
	v_cvt_f32_ubyte1_e32 v193, v185
	v_cvt_f32_ubyte0_e32 v192, v185
	v_cvt_f32_ubyte3_e32 v195, v185
	v_cvt_f32_ubyte2_e32 v194, v185
	v_pk_mul_f32 v[186:187], v[186:187], s[36:37] op_sel_hi:[1,0]
	v_pk_mul_f32 v[188:189], v[188:189], s[36:37] op_sel_hi:[1,0]
	v_pk_mul_f32 v[192:193], v[192:193], s[36:37] op_sel_hi:[1,0]
	v_pk_mul_f32 v[184:185], v[194:195], s[36:37] op_sel_hi:[1,0]
	v_pk_mul_f32 v[186:187], v[68:69], v[186:187]
	v_pk_mul_f32 v[188:189], v[70:71], v[188:189]
	v_pk_mul_f32 v[192:193], v[64:65], v[192:193]
	s_and_b64 vcc, exec, s[4:5]
	v_pk_mul_f32 v[184:185], v[66:67], v[184:185]
	s_cbranch_vccnz .LBB0_926
	v_lshlrev_b32_e32 v194, 16, v128
	v_and_b32_e32 v195, 0xffff0000, v128
	v_pk_add_f32 v[186:187], v[186:187], v[194:195]
	v_lshlrev_b32_e32 v194, 16, v129
	v_and_b32_e32 v195, 0xffff0000, v129
	v_pk_add_f32 v[188:189], v[188:189], v[194:195]
	v_lshlrev_b32_e32 v194, 16, v130
	v_and_b32_e32 v195, 0xffff0000, v130
	v_pk_add_f32 v[192:193], v[192:193], v[194:195]
	v_lshlrev_b32_e32 v194, 16, v131
	v_and_b32_e32 v195, 0xffff0000, v131
	v_pk_add_f32 v[184:185], v[184:185], v[194:195]
	global_load_dwordx4 v[128:131], v[228:229], off offset:2048

; __device__ __forceinline__ void unpack8(const v4u r, float* x) { x[0] = bflo(r.x); x[1] = bfhi(r.x); x[2] = bflo(r.y); x[3] = bfhi(r.y); x[4] = bflo(r.z); x[5] = bfhi(r.z); x[6] = bflo(r.w); x[7] = bfhi(r.w); }
; __device__ __forceinline__ v4u pack8(const float* x) { v4u o; o.x = pk2(x[0], x[1]); o.y = pk2(x[2], x[3]); o.z = pk2(x[4], x[5]); o.w = pk2(x[6], x[7]); return o; }
; __device__ __forceinline__ size_t tl(int row, int col, int K) { return (size_t)(row >> 8) * ((size_t)256 * K) + (size_t)(col >> 6) * (256 * 64) + (size_t)((row & 255) * 64 + (col & 63)); }
;     __device__ __forceinline__ void operator()(const f32x4 (&acc)[2][2][4][2], const Unit& u, int wr, int wc, int, int) const {
;     ...
;         for (int ai = 0; ai < 2; ++ai) {
;             u32x4 mo[4][2];
;             if (br != 0) {
; #pragma unroll
;                 for (int m = 0; m < 4; ++m)
; #pragma unroll
;                     for (int bj = 0; bj < 2; ++bj) mo[m][bj] = *(const u32x4*)(Mg + tl(row0 + ai * HALF + m * 16, col0 + bj * HALF, DM));
;             }
;             asm volatile("" ::: "memory");
; #pragma unroll
;             for (int m = 0; m < 4; ++m) {
;                 const int row = row0 + ai * HALF + m * 16;
; #pragma unroll
;                 for (int bj = 0; bj < 2; ++bj) {
;                     float g[8], o[8];
;                     { const v2u q = gq[ai][m][bj]; const float k = 1.0f / 255.0f;
;                       g[0] = (float)(q.x & 255u) * k; g[1] = (float)((q.x >> 8) & 255u) * k; g[2] = (float)((q.x >> 16) & 255u) * k; g[3] = (float)(q.x >> 24) * k;
;                       g[4] = (float)(q.y & 255u) * k; g[5] = (float)((q.y >> 8) & 255u) * k; g[6] = (float)((q.y >> 16) & 255u) * k; g[7] = (float)(q.y >> 24) * k; }
; #pragma unroll
;                     for (int n = 0; n < 2; ++n)
; #pragma unroll
;                         for (int i = 0; i < 4; ++i) o[n * 4 + i] = g[n * 4 + i] * acc[ai][bj][m][n][i];
;                     if (br != 0) { float p[8]; unpack8(mo[m][bj], p);
; #pragma unroll
;                         for (int i = 0; i < 8; ++i) o[i] += p[i]; }
;                     *(u32x4*)(Mg + tl(row, col0 + bj * HALF, DM)) = pack8(o);
;                 }
.LBB0_928:
	v_cvt_f32_ubyte1_e32 v187, v182
	v_cvt_f32_ubyte0_e32 v186, v182
	v_cvt_f32_ubyte3_e32 v189, v182
	v_cvt_f32_ubyte2_e32 v188, v182
	v_cvt_f32_ubyte1_e32 v191, v183
	v_cvt_f32_ubyte0_e32 v190, v183
	v_cvt_f32_ubyte3_e32 v193, v183
	v_cvt_f32_ubyte2_e32 v192, v183
	v_pk_mul_f32 v[186:187], v[186:187], s[36:37] op_sel_hi:[1,0]
	v_pk_mul_f32 v[188:189], v[188:189], s[36:37] op_sel_hi:[1,0]
	v_pk_mul_f32 v[190:191], v[190:191], s[36:37] op_sel_hi:[1,0]
	v_pk_mul_f32 v[182:183], v[192:193], s[36:37] op_sel_hi:[1,0]
	v_pk_mul_f32 v[186:187], v[60:61], v[186:187]
	v_pk_mul_f32 v[188:189], v[62:63], v[188:189]
	v_pk_mul_f32 v[190:191], v[56:57], v[190:191]
	s_and_b64 vcc, exec, s[4:5]
	v_pk_mul_f32 v[182:183], v[58:59], v[182:183]
	s_cbranch_vccnz .LBB0_930
	s_waitcnt vmcnt(15)
	v_lshlrev_b32_e32 v192, 16, v156
	v_and_b32_e32 v193, 0xffff0000, v156
	v_lshlrev_b32_e32 v156, 16, v157
	v_and_b32_e32 v157, 0xffff0000, v157
	v_pk_add_f32 v[188:189], v[188:189], v[156:157]
	v_lshlrev_b32_e32 v156, 16, v158
	v_and_b32_e32 v157, 0xffff0000, v158
	v_pk_add_f32 v[190:191], v[190:191], v[156:157]
	v_lshlrev_b32_e32 v156, 16, v159
	v_and_b32_e32 v157, 0xffff0000, v159
	v_pk_add_f32 v[186:187], v[186:187], v[192:193]
	v_pk_add_f32 v[182:183], v[182:183], v[156:157]
.LBB0_930:
	v_cvt_pk_bf16_f32 v186, v186, v187
	v_cvt_pk_bf16_f32 v187, v188, v189
	v_cvt_pk_bf16_f32 v188, v190, v191
	v_cvt_pk_bf16_f32 v189, v182, v183
	s_waitcnt vmcnt(15)
	v_lshl_add_u64 v[156:157], v[184:185], 0, v[220:221]
	global_store_dwordx4 v[156:157], v[186:189], off
	v_cvt_f32_ubyte1_e32 v159, v180
	v_cvt_f32_ubyte0_e32 v158, v180
	v_cvt_f32_ubyte3_e32 v183, v180
	v_cvt_f32_ubyte2_e32 v182, v180
	v_cvt_f32_ubyte1_e32 v185, v181
	v_cvt_f32_ubyte0_e32 v184, v181
	v_cvt_f32_ubyte3_e32 v187, v181
	v_cvt_f32_ubyte2_e32 v186, v181
	v_pk_mul_f32 v[158:159], v[158:159], s[36:37] op_sel_hi:[1,0]
	v_pk_mul_f32 v[182:183], v[182:183], s[36:37] op_sel_hi:[1,0]
	v_pk_mul_f32 v[184:185], v[184:185], s[36:37] op_sel_hi:[1,0]
	v_pk_mul_f32 v[180:181], v[186:187], s[36:37] op_sel_hi:[1,0]
	v_pk_mul_f32 v[158:159], v[28:29], v[158:159]
	v_pk_mul_f32 v[182:183], v[30:31], v[182:183]
	v_pk_mul_f32 v[184:185], v[24:25], v[184:185]
	s_and_b64 vcc, exec, s[4:5]
	v_pk_mul_f32 v[180:181], v[26:27], v[180:181]
	s_cbranch_vccnz .LBB0_932
	s_waitcnt vmcnt(12)
	v_lshlrev_b32_e32 v186, 16, v152
	v_and_b32_e32 v187, 0xffff0000, v152
	v_lshlrev_b32_e32 v152, 16, v153
	v_and_b32_e32 v153, 0xffff0000, v153
	v_pk_add_f32 v[182:183], v[182:183], v[152:153]
	v_lshlrev_b32_e32 v152, 16, v154
	v_and_b32_e32 v153, 0xffff0000, v154
	v_pk_add_f32 v[184:185], v[184:185], v[152:153]
	v_lshlrev_b32_e32 v152, 16, v155
	v_and_b32_e32 v153, 0xffff0000, v155
	v_pk_add_f32 v[158:159], v[158:159], v[186:187]
	v_pk_add_f32 v[180:181], v[180:181], v[152:153]
.LBB0_932:
	v_cvt_pk_bf16_f32 v186, v158, v159
	v_cvt_pk_bf16_f32 v187, v182, v183
	v_cvt_pk_bf16_f32 v189, v180, v181
	s_waitcnt vmcnt(12)
	v_add_co_u32_e32 v152, vcc, s81, v156
	v_cvt_f32_ubyte1_e32 v155, v178
	v_cvt_f32_ubyte0_e32 v154, v178
	v_cvt_f32_ubyte3_e32 v159, v178
	v_cvt_f32_ubyte2_e32 v158, v178
	v_cvt_f32_ubyte1_e32 v181, v179
	v_cvt_f32_ubyte0_e32 v180, v179
	v_cvt_f32_ubyte3_e32 v183, v179
	v_cvt_f32_ubyte2_e32 v182, v179
	v_addc_co_u32_e32 v153, vcc, 0, v157, vcc
	v_pk_mul_f32 v[154:155], v[154:155], s[36:37] op_sel_hi:[1,0]
	v_pk_mul_f32 v[158:159], v[158:159], s[36:37] op_sel_hi:[1,0]
	v_pk_mul_f32 v[180:181], v[180:181], s[36:37] op_sel_hi:[1,0]
	v_pk_mul_f32 v[178:179], v[182:183], s[36:37] op_sel_hi:[1,0]
	v_cvt_pk_bf16_f32 v188, v184, v185
	v_pk_mul_f32 v[154:155], v[52:53], v[154:155]
	v_pk_mul_f32 v[158:159], v[54:55], v[158:159]
	v_pk_mul_f32 v[180:181], v[48:49], v[180:181]
	s_and_b64 vcc, exec, s[4:5]
	v_pk_mul_f32 v[178:179], v[50:51], v[178:179]
	global_store_dwordx4 v[152:153], v[186:189], off
	s_cbranch_vccnz .LBB0_934
	v_lshlrev_b32_e32 v182, 16, v148
	v_and_b32_e32 v183, 0xffff0000, v148
	v_lshlrev_b32_e32 v148, 16, v149
	v_and_b32_e32 v149, 0xffff0000, v149
	v_pk_add_f32 v[158:159], v[158:159], v[148:149]
	v_lshlrev_b32_e32 v148, 16, v150
	v_and_b32_e32 v149, 0xffff0000, v150
	v_pk_add_f32 v[180:181], v[180:181], v[148:149]
	v_lshlrev_b32_e32 v148, 16, v151
	v_and_b32_e32 v149, 0xffff0000, v151
	v_pk_add_f32 v[154:155], v[154:155], v[182:183]
	v_pk_add_f32 v[178:179], v[178:179], v[148:149]
.LBB0_934:
	v_cvt_pk_bf16_f32 v148, v154, v155
	v_cvt_pk_bf16_f32 v149, v158, v159
	v_cvt_pk_bf16_f32 v150, v180, v181
	v_cvt_pk_bf16_f32 v151, v178, v179
	global_store_dwordx4 v[156:157], v[148:151], off offset:2048
	v_cvt_f32_ubyte1_e32 v155, v177
	v_cvt_f32_ubyte0_e32 v154, v177
	v_cvt_f32_ubyte1_e32 v149, v176
	v_cvt_f32_ubyte0_e32 v148, v176
	v_cvt_f32_ubyte3_e32 v151, v176
	v_cvt_f32_ubyte2_e32 v150, v176
	v_cvt_f32_ubyte3_e32 v159, v177
	v_cvt_f32_ubyte2_e32 v158, v177
	v_pk_mul_f32 v[148:149], v[148:149], s[36:37] op_sel_hi:[1,0]
	v_pk_mul_f32 v[150:151], v[150:151], s[36:37] op_sel_hi:[1,0]
	v_pk_mul_f32 v[154:155], v[154:155], s[36:37] op_sel_hi:[1,0]
	v_pk_mul_f32 v[158:159], v[158:159], s[36:37] op_sel_hi:[1,0]
	v_pk_mul_f32 v[148:149], v[20:21], v[148:149]
	v_pk_mul_f32 v[150:151], v[22:23], v[150:151]
	v_pk_mul_f32 v[154:155], v[16:17], v[154:155]
	s_and_b64 vcc, exec, s[4:5]
	v_pk_mul_f32 v[158:159], v[18:19], v[158:159]
	s_cbranch_vccnz .LBB0_936
	s_waitcnt vmcnt(12)
	v_lshlrev_b32_e32 v176, 16, v144
	v_and_b32_e32 v177, 0xffff0000, v144
	v_lshlrev_b32_e32 v144, 16, v145
	v_and_b32_e32 v145, 0xffff0000, v145
	v_pk_add_f32 v[150:151], v[150:151], v[144:145]
	v_lshlrev_b32_e32 v144, 16, v146
	v_and_b32_e32 v145, 0xffff0000, v146
	v_pk_add_f32 v[154:155], v[154:155], v[144:145]
	v_lshlrev_b32_e32 v144, 16, v147
	v_and_b32_e32 v145, 0xffff0000, v147
	v_pk_add_f32 v[148:149], v[148:149], v[176:177]
	v_pk_add_f32 v[158:159], v[158:159], v[144:145]
; __device__ __forceinline__ void unpack8(const v4u r, float* x) { x[0] = bflo(r.x); x[1] = bfhi(r.x); x[2] = bflo(r.y); x[3] = bfhi(r.y); x[4] = bflo(r.z); x[5] = bfhi(r.z); x[6] = bflo(r.w); x[7] = bfhi(r.w); }
; __device__ __forceinline__ v4u pack8(const float* x) { v4u o; o.x = pk2(x[0], x[1]); o.y = pk2(x[2], x[3]); o.z = pk2(x[4], x[5]); o.w = pk2(x[6], x[7]); return o; }
; __device__ __forceinline__ size_t tl(int row, int col, int K) { return (size_t)(row >> 8) * ((size_t)256 * K) + (size_t)(col >> 6) * (256 * 64) + (size_t)((row & 255) * 64 + (col & 63)); }
;     __device__ __forceinline__ void operator()(const f32x4 (&acc)[2][2][4][2], const Unit& u, int wr, int wc, int, int) const {
;     ...
;             for (int m = 0; m < 4; ++m) {
;                 const int row = row0 + ai * HALF + m * 16;
; #pragma unroll
;                 for (int bj = 0; bj < 2; ++bj) {
;                     float g[8], o[8];
;                     { const v2u q = gq[ai][m][bj]; const float k = 1.0f / 255.0f;
;                       g[0] = (float)(q.x & 255u) * k; g[1] = (float)((q.x >> 8) & 255u) * k; g[2] = (float)((q.x >> 16) & 255u) * k; g[3] = (float)(q.x >> 24) * k;
;                       g[4] = (float)(q.y & 255u) * k; g[5] = (float)((q.y >> 8) & 255u) * k; g[6] = (float)((q.y >> 16) & 255u) * k; g[7] = (float)(q.y >> 24) * k; }
; #pragma unroll
;                     for (int n = 0; n < 2; ++n)
; #pragma unroll
;                         for (int i = 0; i < 4; ++i) o[n * 4 + i] = g[n * 4 + i] * acc[ai][bj][m][n][i];
;                     if (br != 0) { float p[8]; unpack8(mo[m][bj], p);
; #pragma unroll
;                         for (int i = 0; i < 8; ++i) o[i] += p[i]; }
;                     *(u32x4*)(Mg + tl(row, col0 + bj * HALF, DM)) = pack8(o);
;                 }
.LBB0_936:
	s_waitcnt vmcnt(12)
	v_cvt_pk_bf16_f32 v144, v148, v149
	v_cvt_pk_bf16_f32 v145, v150, v151
	v_cvt_pk_bf16_f32 v146, v154, v155
	v_cvt_pk_bf16_f32 v147, v158, v159
	global_store_dwordx4 v[152:153], v[144:147], off offset:2048
	v_cvt_f32_ubyte1_e32 v149, v175
	v_cvt_f32_ubyte0_e32 v148, v175
	v_cvt_f32_ubyte1_e32 v145, v174
	v_cvt_f32_ubyte0_e32 v144, v174
	v_cvt_f32_ubyte3_e32 v147, v174
	v_cvt_f32_ubyte2_e32 v146, v174
	v_cvt_f32_ubyte3_e32 v151, v175
	v_cvt_f32_ubyte2_e32 v150, v175
	v_pk_mul_f32 v[144:145], v[144:145], s[36:37] op_sel_hi:[1,0]
	v_pk_mul_f32 v[146:147], v[146:147], s[36:37] op_sel_hi:[1,0]
	v_pk_mul_f32 v[148:149], v[148:149], s[36:37] op_sel_hi:[1,0]
	v_pk_mul_f32 v[150:151], v[150:151], s[36:37] op_sel_hi:[1,0]
	v_pk_mul_f32 v[144:145], v[44:45], v[144:145]
	v_pk_mul_f32 v[146:147], v[46:47], v[146:147]
	v_pk_mul_f32 v[148:149], v[40:41], v[148:149]
	s_and_b64 vcc, exec, s[4:5]
	v_pk_mul_f32 v[150:151], v[42:43], v[150:151]
	s_cbranch_vccnz .LBB0_938
	s_waitcnt vmcnt(11)
	v_lshlrev_b32_e32 v152, 16, v140
	v_and_b32_e32 v153, 0xffff0000, v140
	v_lshlrev_b32_e32 v140, 16, v141
	v_and_b32_e32 v141, 0xffff0000, v141
	v_pk_add_f32 v[146:147], v[146:147], v[140:141]
	v_lshlrev_b32_e32 v140, 16, v142
	v_and_b32_e32 v141, 0xffff0000, v142
	v_pk_add_f32 v[148:149], v[148:149], v[140:141]
	v_lshlrev_b32_e32 v140, 16, v143
	v_and_b32_e32 v141, 0xffff0000, v143
	v_pk_add_f32 v[144:145], v[144:145], v[152:153]
	v_pk_add_f32 v[150:151], v[150:151], v[140:141]
.LBB0_938:
	s_waitcnt vmcnt(11)
	v_add_co_u32_e32 v140, vcc, s85, v156
	v_cvt_pk_bf16_f32 v142, v144, v145
	v_cvt_pk_bf16_f32 v143, v146, v147
	v_cvt_pk_bf16_f32 v144, v148, v149
	v_cvt_pk_bf16_f32 v145, v150, v151
	v_addc_co_u32_e32 v141, vcc, 0, v157, vcc
	global_store_dwordx4 v[140:141], v[142:145], off
	v_cvt_f32_ubyte1_e32 v147, v173
	v_cvt_f32_ubyte0_e32 v146, v173
	v_cvt_f32_ubyte1_e32 v143, v172
	v_cvt_f32_ubyte0_e32 v142, v172
	v_cvt_f32_ubyte3_e32 v145, v172
	v_cvt_f32_ubyte2_e32 v144, v172
	v_cvt_f32_ubyte3_e32 v149, v173
	v_cvt_f32_ubyte2_e32 v148, v173
	v_pk_mul_f32 v[142:143], v[142:143], s[36:37] op_sel_hi:[1,0]
	v_pk_mul_f32 v[144:145], v[144:145], s[36:37] op_sel_hi:[1,0]
	v_pk_mul_f32 v[146:147], v[146:147], s[36:37] op_sel_hi:[1,0]
	v_pk_mul_f32 v[148:149], v[148:149], s[36:37] op_sel_hi:[1,0]
	v_pk_mul_f32 v[142:143], v[12:13], v[142:143]
	v_pk_mul_f32 v[144:145], v[14:15], v[144:145]
	v_pk_mul_f32 v[146:147], v[8:9], v[146:147]
	s_and_b64 vcc, exec, s[4:5]
	v_pk_mul_f32 v[148:149], v[10:11], v[148:149]
	s_cbranch_vccnz .LBB0_940
	s_waitcnt vmcnt(8)
	v_lshlrev_b32_e32 v150, 16, v136
	v_and_b32_e32 v151, 0xffff0000, v136
	v_lshlrev_b32_e32 v136, 16, v137
	v_and_b32_e32 v137, 0xffff0000, v137
	v_pk_add_f32 v[144:145], v[144:145], v[136:137]
	v_lshlrev_b32_e32 v136, 16, v138
	v_and_b32_e32 v137, 0xffff0000, v138
	v_pk_add_f32 v[146:147], v[146:147], v[136:137]
	v_lshlrev_b32_e32 v136, 16, v139
	v_and_b32_e32 v137, 0xffff0000, v139
	v_pk_add_f32 v[142:143], v[142:143], v[150:151]
	v_pk_add_f32 v[148:149], v[148:149], v[136:137]
.LBB0_940:
	s_waitcnt vmcnt(8)
	v_cvt_pk_bf16_f32 v136, v142, v143
	v_add_co_u32_e32 v142, vcc, s11, v156
	v_cvt_pk_bf16_f32 v137, v144, v145
	v_cvt_pk_bf16_f32 v138, v146, v147
	v_cvt_pk_bf16_f32 v139, v148, v149
	v_addc_co_u32_e32 v143, vcc, 0, v157, vcc
	global_store_dwordx4 v[142:143], v[136:139], off
	v_cvt_f32_ubyte1_e32 v143, v171
	v_cvt_f32_ubyte0_e32 v142, v171
	v_cvt_f32_ubyte1_e32 v137, v170
	v_cvt_f32_ubyte0_e32 v136, v170
	v_cvt_f32_ubyte3_e32 v139, v170
	v_cvt_f32_ubyte2_e32 v138, v170
	v_cvt_f32_ubyte3_e32 v145, v171
	v_cvt_f32_ubyte2_e32 v144, v171
	v_pk_mul_f32 v[136:137], v[136:137], s[36:37] op_sel_hi:[1,0]
	v_pk_mul_f32 v[138:139], v[138:139], s[36:37] op_sel_hi:[1,0]
	v_pk_mul_f32 v[142:143], v[142:143], s[36:37] op_sel_hi:[1,0]
	v_pk_mul_f32 v[144:145], v[144:145], s[36:37] op_sel_hi:[1,0]
	v_pk_mul_f32 v[136:137], v[36:37], v[136:137]
	v_pk_mul_f32 v[138:139], v[38:39], v[138:139]
	v_pk_mul_f32 v[142:143], v[32:33], v[142:143]
	s_and_b64 vcc, exec, s[4:5]
	v_pk_mul_f32 v[144:145], v[34:35], v[144:145]
	s_cbranch_vccnz .LBB0_942
	v_lshlrev_b32_e32 v146, 16, v132
	v_and_b32_e32 v147, 0xffff0000, v132
	v_lshlrev_b32_e32 v132, 16, v133
	v_and_b32_e32 v133, 0xffff0000, v133
	v_pk_add_f32 v[138:139], v[138:139], v[132:133]
	v_lshlrev_b32_e32 v132, 16, v134
	v_and_b32_e32 v133, 0xffff0000, v134
	v_pk_add_f32 v[142:143], v[142:143], v[132:133]
	v_lshlrev_b32_e32 v132, 16, v135
	v_and_b32_e32 v133, 0xffff0000, v135
	v_pk_add_f32 v[136:137], v[136:137], v[146:147]
	v_pk_add_f32 v[144:145], v[144:145], v[132:133]
.LBB0_942:
	v_cvt_pk_bf16_f32 v132, v136, v137
	v_cvt_pk_bf16_f32 v133, v138, v139
	v_cvt_pk_bf16_f32 v134, v142, v143
	v_cvt_pk_bf16_f32 v135, v144, v145
	global_store_dwordx4 v[140:141], v[132:135], off offset:2048
	v_cvt_f32_ubyte1_e32 v137, v169
	v_cvt_f32_ubyte0_e32 v136, v169
	v_cvt_f32_ubyte1_e32 v133, v168
	v_cvt_f32_ubyte0_e32 v132, v168
	v_cvt_f32_ubyte3_e32 v135, v168
	v_cvt_f32_ubyte2_e32 v134, v168
	v_cvt_f32_ubyte3_e32 v139, v169
	v_cvt_f32_ubyte2_e32 v138, v169
	v_pk_mul_f32 v[132:133], v[132:133], s[36:37] op_sel_hi:[1,0]
	v_pk_mul_f32 v[134:135], v[134:135], s[36:37] op_sel_hi:[1,0]
	v_pk_mul_f32 v[136:137], v[136:137], s[36:37] op_sel_hi:[1,0]
	v_pk_mul_f32 v[138:139], v[138:139], s[36:37] op_sel_hi:[1,0]
	v_pk_mul_f32 v[132:133], v[4:5], v[132:133]
	v_pk_mul_f32 v[134:135], v[6:7], v[134:135]
	v_pk_mul_f32 v[136:137], v[0:1], v[136:137]
	s_and_b64 vcc, exec, s[4:5]
	v_pk_mul_f32 v[138:139], v[2:3], v[138:139]
	s_cbranch_vccnz .LBB0_944
	s_waitcnt vmcnt(8)
	v_lshlrev_b32_e32 v140, 16, v128
	v_and_b32_e32 v141, 0xffff0000, v128
	v_lshlrev_b32_e32 v128, 16, v129
	v_and_b32_e32 v129, 0xffff0000, v129
	v_pk_add_f32 v[134:135], v[134:135], v[128:129]
	v_lshlrev_b32_e32 v128, 16, v130
	v_and_b32_e32 v129, 0xffff0000, v130
	v_pk_add_f32 v[136:137], v[136:137], v[128:129]
	v_lshlrev_b32_e32 v128, 16, v131
	v_and_b32_e32 v129, 0xffff0000, v131
	v_pk_add_f32 v[132:133], v[132:133], v[140:141]
	v_pk_add_f32 v[138:139], v[138:139], v[128:129]
.LBB0_944:
	s_waitcnt vmcnt(8)
	v_cvt_pk_bf16_f32 v128, v132, v133
	v_add_co_u32_e32 v132, vcc, 0x11000, v156
	v_cvt_pk_bf16_f32 v129, v134, v135
	v_cvt_pk_bf16_f32 v130, v136, v137
	v_cvt_pk_bf16_f32 v131, v138, v139
	v_addc_co_u32_e32 v133, vcc, 0, v157, vcc
	global_store_dwordx4 v[132:133], v[128:131], off offset:2048
